# seam between FFN-in and FFN-out GEMMs uses a 4-workgroup local barrier (row-tile owners, same XCD) instead of the full grid barrier
# baseline (speedup 1.0000x reference)
_Z14fwd_megakernel4Args:
	s_mov_b32 s101, 0
	s_load_dwordx8 s[8:15], s[0:1], 0x0
	s_load_dwordx4 s[24:27], s[0:1], 0x20
	s_load_dwordx2 s[6:7], s[0:1], 0x30
	s_mov_b64 s[30:31], s[0:1]
	s_load_dwordx4 s[64:67], s[0:1], 0xb0
	s_load_dwordx2 s[72:73], s[0:1], 0xb0
	s_add_u32 s28, s30, 0xb8
	v_and_b32_e32 v156, 0x3ff, v0
	s_mov_b32 s74, s2
	s_addc_u32 s29, s31, 0
	v_readfirstlane_b32 s2, v156
	v_cmp_gt_u32_e32 vcc, 2, v156
	s_and_saveexec_b64 s[0:1], vcc
	v_lshl_add_u32 v1, v156, 2, 0
	v_add_u32_e32 v1, 0x23fc0, v1
	v_mov_b32_e32 v2, 0
	ds_write_b32 v1, v2
	s_or_b64 exec, exec, s[0:1]
	s_cmp_lg_u32 s74, 0
	s_mov_b32 s0, 0
	s_cbranch_scc1 .LBB0_10
	v_sub_u32_e32 v1, 0xd7f, v156
	v_lshrrev_b32_e32 v2, 9, v1
	v_add_u32_e32 v1, 2, v2
	v_add_u32_e32 v157, 0x200, v156
	v_and_b32_e32 v3, 14, v1
	v_mov_b32_e32 v1, v2
	s_mov_b64 s[16:17], 0
	s_mov_b32 s1, 1
	v_mov_b32_e32 v5, 0
	s_mov_b32 s18, s0
	v_mov_b64_e32 v[6:7], v[156:157]
	s_branch .LBB0_5

.LBB0_176:
	s_waitcnt vmcnt(0)
	s_waitcnt vmcnt(0)
	s_barrier
	s_mov_b64 s[26:27], exec
	v_readlane_b32 s28, v241, 4
	v_readlane_b32 s29, v241, 5
	s_and_b64 s[28:29], s[26:27], s[28:29]
	s_xor_b64 s[26:27], s[28:29], s[26:27]
	s_mov_b64 exec, s[28:29]
	s_cbranch_execz .LBB0_229
	s_add_u32 s101, s101, 4
	s_and_b32 s34, s74, 63
	s_and_b32 s35, s34, 7
	s_lshl_b32 s35, s35, 2
	s_lshr_b32 s36, s34, 4
	s_add_u32 s35, s35, s36
	s_lshl_b32 s35, s35, 8
	s_lshr_b32 s36, s34, 3
	s_and_b32 s36, s36, 1
	s_lshl_b32 s36, s36, 6
	s_add_u32 s35, s35, s36
	s_add_u32 s35, s35, 0x480
	v_mov_b32_e32 v0, s35
	v_mov_b32_e32 v1, 1
	s_waitcnt vmcnt(0) lgkmcnt(0)
	global_atomic_add v0, v1, s[72:73]
	s_mov_b32 s19, 0
.Lgrp_poll_a:
	global_load_dword v3, v0, s[72:73] sc1
	s_waitcnt vmcnt(0)
	v_readfirstlane_b32 s34, v3
	s_sub_u32 s34, s34, s101
	s_cmp_ge_i32 s34, 0
	s_cbranch_scc1 .Lgrp_done_a
	s_sleep 1
	s_add_u32 s19, s19, 1
	s_cmp_lt_u32 s19, 0x400000
	s_cbranch_scc1 .Lgrp_poll_a
.Lgrp_done_a:
	buffer_inv sc1
	s_waitcnt vmcnt(0)
